# grid barrier rewritten by hand for the 20 in-loop instances: one release hop (last XCD leader bumps 256 private per-workgroup flags), each WG polls its own flag; census/first barrier unchanged
# speedup vs baseline: 1.0307x; 1.0082x over previous
.Ltail_end:
.LBB0_175:
	v_readlane_b32 s4, v254, 49
	s_add_i32 s14, s4, 2
	v_readlane_b32 s4, v252, 9
	v_readlane_b32 s5, v252, 10
	s_cmp_ge_i32 s14, s5
	s_waitcnt lgkmcnt(0)
	s_barrier
	s_cbranch_scc1 .LBB0_229
	s_waitcnt vmcnt(0)
	s_barrier
	s_mov_b64 s[4:5], exec
	v_readlane_b32 s6, v252, 31
	v_readlane_b32 s7, v252, 32
	s_mul_i32 s72, s62, 5
	s_add_i32 s72, s72, 2
	s_and_b64 s[6:7], s[4:5], s[6:7]
	s_mov_b64 exec, s[6:7]
	s_cbranch_execz .LBB0_228
	v_readlane_b32 s10, v253, 57
	v_readlane_b32 s11, v253, 58
	v_readlane_b32 s73, v254, 38
	v_mov_b32_e32 v2, 1
	s_nop 4
	global_atomic_add v3, v1, v2, s[10:11] sc0
	v_mov_b32_e32 v0, s73
	v_readlane_b32 s73, v254, 39
	ds_read_b32 v4, v0
	s_nop 1
	v_mov_b32_e32 v0, s73
	ds_read_b32 v5, v0
	s_waitcnt lgkmcnt(0)
	v_mul_lo_u32 v4, v4, s72
	v_mul_lo_u32 v5, v5, s72
	s_waitcnt vmcnt(0)
	v_add_u32_e32 v3, 1, v3
	v_cmp_eq_u32_e32 vcc, v3, v4
	s_cbranch_vccz .Lxb1_poll
	buffer_wbl2 sc1
	v_readlane_b32 s10, v253, 61
	v_readlane_b32 s11, v253, 62
	s_waitcnt vmcnt(0)
	s_nop 4
	global_atomic_add v3, v1, v2, s[10:11] sc0
	s_waitcnt vmcnt(0)
	v_add_u32_e32 v3, 1, v3
	v_cmp_eq_u32_e32 vcc, v3, v5
	s_cbranch_vccz .Lxb1_poll
	s_add_u32 s10, s30, 0x8400
	s_addc_u32 s11, s31, 0
	s_mov_b64 exec, -1
	v_mbcnt_lo_u32_b32 v3, -1, 0
	v_mbcnt_hi_u32_b32 v3, -1, v3
	v_mov_b32_e32 v2, 1
	v_lshlrev_b32_e32 v3, 5, v3
	s_nop 1
	global_atomic_add v3, v2, s[10:11]
	global_atomic_add v3, v2, s[10:11] offset:2048
	s_add_u32 s10, s10, 0x1000
	s_addc_u32 s11, s11, 0
	global_atomic_add v3, v2, s[10:11]
	global_atomic_add v3, v2, s[10:11] offset:2048
	s_mov_b64 exec, s[6:7]
.Lxb1_poll:
	v_readlane_b32 s10, v252, 0
	s_sub_u32 s73, s72, 1
	s_lshl_b32 s10, s10, 5
	s_add_u32 s10, s10, 0x8400
	s_add_u32 s10, s30, s10
	s_addc_u32 s11, s31, 0
.Lxb1_spin:
	global_load_dword v3, v1, s[10:11] sc1
	s_waitcnt vmcnt(0)
	v_cmp_le_u32_e32 vcc, s73, v3
	s_cbranch_vccnz .Lxb1_acq
	s_sleep 1
	s_branch .Lxb1_spin
.Lxb1_acq:
	buffer_inv sc1
	s_waitcnt vmcnt(0)

.LBB0_250:
	v_readlane_b32 s4, v254, 49
	s_add_i32 s14, s4, 3
	v_readlane_b32 s4, v252, 9
	v_readlane_b32 s5, v252, 10
	s_cmp_ge_i32 s14, s5
	s_cbranch_scc1 .LBB0_304
	s_waitcnt vmcnt(0)
	s_waitcnt lgkmcnt(0)
	s_barrier
	s_mov_b64 s[4:5], exec
	v_readlane_b32 s6, v252, 31
	v_readlane_b32 s7, v252, 32
	s_mul_i32 s72, s62, 5
	s_add_i32 s72, s72, 3
	s_and_b64 s[6:7], s[4:5], s[6:7]
	s_mov_b64 exec, s[6:7]
	s_cbranch_execz .LBB0_303
	v_readlane_b32 s10, v253, 57
	v_readlane_b32 s11, v253, 58
	v_readlane_b32 s73, v254, 38
	v_mov_b32_e32 v2, 1
	s_nop 4
	global_atomic_add v3, v1, v2, s[10:11] sc0
	v_mov_b32_e32 v0, s73
	v_readlane_b32 s73, v254, 39
	ds_read_b32 v4, v0
	s_nop 1
	v_mov_b32_e32 v0, s73
	ds_read_b32 v5, v0
	s_waitcnt lgkmcnt(0)
	v_mul_lo_u32 v4, v4, s72
	v_mul_lo_u32 v5, v5, s72
	s_waitcnt vmcnt(0)
	v_add_u32_e32 v3, 1, v3
	v_cmp_eq_u32_e32 vcc, v3, v4
	s_cbranch_vccz .Lxb2_poll
	buffer_wbl2 sc1
	v_readlane_b32 s10, v253, 61
	v_readlane_b32 s11, v253, 62
	s_waitcnt vmcnt(0)
	s_nop 4
	global_atomic_add v3, v1, v2, s[10:11] sc0
	s_waitcnt vmcnt(0)
	v_add_u32_e32 v3, 1, v3
	v_cmp_eq_u32_e32 vcc, v3, v5
	s_cbranch_vccz .Lxb2_poll
	s_add_u32 s10, s30, 0x8400
	s_addc_u32 s11, s31, 0
	s_mov_b64 exec, -1
	v_mbcnt_lo_u32_b32 v3, -1, 0
	v_mbcnt_hi_u32_b32 v3, -1, v3
	v_mov_b32_e32 v2, 1
	v_lshlrev_b32_e32 v3, 5, v3
	s_nop 1
	global_atomic_add v3, v2, s[10:11]
	global_atomic_add v3, v2, s[10:11] offset:2048
	s_add_u32 s10, s10, 0x1000
	s_addc_u32 s11, s11, 0
	global_atomic_add v3, v2, s[10:11]
	global_atomic_add v3, v2, s[10:11] offset:2048
	s_mov_b64 exec, s[6:7]

.LBB0_409:
	v_readlane_b32 s4, v254, 49
	s_add_i32 s14, s4, 4
	v_readlane_b32 s4, v252, 9
	v_readlane_b32 s5, v252, 10
	s_cmp_ge_i32 s14, s5
	s_cbranch_scc1 .LBB0_421
	s_waitcnt vmcnt(0)
	s_barrier
	s_mov_b32 s53, 0x2aaaaaab
	s_mov_b32 s62, s70
	s_mov_b64 s[4:5], exec
	v_readlane_b32 s6, v252, 31
	v_readlane_b32 s7, v252, 32
	s_mul_i32 s72, s62, 5
	s_add_i32 s72, s72, 4
	s_and_b64 s[6:7], s[4:5], s[6:7]
	s_mov_b64 exec, s[6:7]
	s_cbranch_execz .LBB0_463
	v_readlane_b32 s10, v253, 57
	v_readlane_b32 s11, v253, 58
	v_readlane_b32 s73, v254, 38
	v_mov_b32_e32 v2, 1
	s_nop 4
	global_atomic_add v3, v1, v2, s[10:11] sc0
	v_mov_b32_e32 v0, s73
	v_readlane_b32 s73, v254, 39
	ds_read_b32 v4, v0
	s_nop 1
	v_mov_b32_e32 v0, s73
	ds_read_b32 v5, v0
	s_waitcnt lgkmcnt(0)
	v_mul_lo_u32 v4, v4, s72
	v_mul_lo_u32 v5, v5, s72
	s_waitcnt vmcnt(0)
	v_add_u32_e32 v3, 1, v3
	v_cmp_eq_u32_e32 vcc, v3, v4
	s_cbranch_vccz .Lxb3_poll
	buffer_wbl2 sc1
	v_readlane_b32 s10, v253, 61
	v_readlane_b32 s11, v253, 62
	s_waitcnt vmcnt(0)
	s_nop 4
	global_atomic_add v3, v1, v2, s[10:11] sc0
	s_waitcnt vmcnt(0)
	v_add_u32_e32 v3, 1, v3
	v_cmp_eq_u32_e32 vcc, v3, v5
	s_cbranch_vccz .Lxb3_poll
	s_add_u32 s10, s30, 0x8400
	s_addc_u32 s11, s31, 0
	s_mov_b64 exec, -1
	v_mbcnt_lo_u32_b32 v3, -1, 0
	v_mbcnt_hi_u32_b32 v3, -1, v3
	v_mov_b32_e32 v2, 1
	v_lshlrev_b32_e32 v3, 5, v3
	s_nop 1
	global_atomic_add v3, v2, s[10:11]
	global_atomic_add v3, v2, s[10:11] offset:2048
	s_add_u32 s10, s10, 0x1000
	s_addc_u32 s11, s11, 0
	global_atomic_add v3, v2, s[10:11]
	global_atomic_add v3, v2, s[10:11] offset:2048
	s_mov_b64 exec, s[6:7]

.Lxb3_acq:
	buffer_inv sc1
	s_waitcnt vmcnt(0)
	s_branch .LBB0_463
.LBB0_421:
	s_mov_b32 s53, 0x2aaaaaab
	s_mov_b32 s62, s70
	s_branch .LBB0_464
.LBB0_463:
	s_or_b64 exec, exec, s[4:5]
	s_waitcnt lgkmcnt(0)
	s_barrier

.LBB0_510:
	s_or_b64 exec, exec, s[10:11]
	v_readlane_b32 s4, v254, 49
	s_add_i32 s8, s4, 5
	v_readlane_b32 s4, v252, 9
	v_readlane_b32 s5, v252, 10
	s_cmp_ge_i32 s8, s5
	s_cbranch_scc1 .LBB0_564
	s_waitcnt vmcnt(0)
	s_waitcnt lgkmcnt(0)
	s_barrier
	s_mov_b64 s[4:5], exec
	v_readlane_b32 s6, v252, 31
	v_readlane_b32 s7, v252, 32
	s_mul_i32 s72, s62, 5
	s_add_i32 s72, s72, 5
	s_and_b64 s[6:7], s[4:5], s[6:7]
	s_mov_b64 exec, s[6:7]
	s_cbranch_execz .LBB0_563
	v_readlane_b32 s10, v253, 57
	v_readlane_b32 s11, v253, 58
	v_readlane_b32 s73, v254, 38
	v_mov_b32_e32 v2, 1
	s_nop 4
	global_atomic_add v3, v1, v2, s[10:11] sc0
	v_mov_b32_e32 v0, s73
	v_readlane_b32 s73, v254, 39
	ds_read_b32 v4, v0
	s_nop 1
	v_mov_b32_e32 v0, s73
	ds_read_b32 v5, v0
	s_waitcnt lgkmcnt(0)
	v_mul_lo_u32 v4, v4, s72
	v_mul_lo_u32 v5, v5, s72
	s_waitcnt vmcnt(0)
	v_add_u32_e32 v3, 1, v3
	v_cmp_eq_u32_e32 vcc, v3, v4
	s_cbranch_vccz .Lxb4_poll
	buffer_wbl2 sc1
	v_readlane_b32 s10, v253, 61
	v_readlane_b32 s11, v253, 62
	s_waitcnt vmcnt(0)
	s_nop 4
	global_atomic_add v3, v1, v2, s[10:11] sc0
	s_waitcnt vmcnt(0)
	v_add_u32_e32 v3, 1, v3
	v_cmp_eq_u32_e32 vcc, v3, v5
	s_cbranch_vccz .Lxb4_poll
	s_add_u32 s10, s30, 0x8400
	s_addc_u32 s11, s31, 0
	s_mov_b64 exec, -1
	v_mbcnt_lo_u32_b32 v3, -1, 0
	v_mbcnt_hi_u32_b32 v3, -1, v3
	v_mov_b32_e32 v2, 1
	v_lshlrev_b32_e32 v3, 5, v3
	s_nop 1
	global_atomic_add v3, v2, s[10:11]
	global_atomic_add v3, v2, s[10:11] offset:2048
	s_add_u32 s10, s10, 0x1000
	s_addc_u32 s11, s11, 0
	global_atomic_add v3, v2, s[10:11]
	global_atomic_add v3, v2, s[10:11] offset:2048
	s_mov_b64 exec, s[6:7]

.Lbar5_entry:
	s_waitcnt vmcnt(0)
	s_barrier
	s_cmp_eq_u32 s62, -1
	s_cbranch_scc0 .Lxb5_lean
	s_mov_b64 s[4:5], exec
	v_readlane_b32 s6, v252, 31
	v_readlane_b32 s7, v252, 32
	s_and_b64 s[6:7], s[4:5], s[6:7]
	s_mov_b64 exec, s[6:7]
	s_cbranch_execz .LBB0_113
	v_readlane_b32 s6, v254, 38
	s_waitcnt vmcnt(0) expcnt(0) lgkmcnt(0)
	s_nop 0
	v_mov_b32_e32 v0, s6
	ds_read_b32 v3, v0
	v_readlane_b32 s6, v254, 39
	s_waitcnt lgkmcnt(0)
	v_cmp_ne_u32_e32 vcc, 0, v3
	v_mov_b32_e32 v0, s6
	ds_read_b32 v2, v0
	s_cbranch_vccnz .LBB0_682
	s_mov_b32 s14, 1
	s_branch .LBB0_670

.Lxb5_lean:
	s_mov_b64 s[4:5], exec
	v_readlane_b32 s6, v252, 31
	v_readlane_b32 s7, v252, 32
	s_mul_i32 s72, s62, 5
	s_add_i32 s72, s72, 6
	s_and_b64 s[6:7], s[4:5], s[6:7]
	s_mov_b64 exec, s[6:7]
	s_cbranch_execz .LBB0_113
	v_readlane_b32 s10, v253, 57
	v_readlane_b32 s11, v253, 58
	v_readlane_b32 s73, v254, 38
	v_mov_b32_e32 v2, 1
	s_nop 4
	global_atomic_add v3, v1, v2, s[10:11] sc0
	v_mov_b32_e32 v0, s73
	v_readlane_b32 s73, v254, 39
	ds_read_b32 v4, v0
	s_nop 1
	v_mov_b32_e32 v0, s73
	ds_read_b32 v5, v0
	s_waitcnt lgkmcnt(0)
	v_mul_lo_u32 v4, v4, s72
	v_mul_lo_u32 v5, v5, s72
	s_waitcnt vmcnt(0)
	v_add_u32_e32 v3, 1, v3
	v_cmp_eq_u32_e32 vcc, v3, v4
	s_cbranch_vccz .Lxb5_poll
	buffer_wbl2 sc1
	v_readlane_b32 s10, v253, 61
	v_readlane_b32 s11, v253, 62
	s_waitcnt vmcnt(0)
	s_nop 4
	global_atomic_add v3, v1, v2, s[10:11] sc0
	s_waitcnt vmcnt(0)
	v_add_u32_e32 v3, 1, v3
	v_cmp_eq_u32_e32 vcc, v3, v5
	s_cbranch_vccz .Lxb5_poll
	s_add_u32 s10, s30, 0x8400
	s_addc_u32 s11, s31, 0
	s_mov_b64 exec, -1
	v_mbcnt_lo_u32_b32 v3, -1, 0
	v_mbcnt_hi_u32_b32 v3, -1, v3
	v_mov_b32_e32 v2, 1
	v_lshlrev_b32_e32 v3, 5, v3
	s_nop 1
	global_atomic_add v3, v2, s[10:11]
	global_atomic_add v3, v2, s[10:11] offset:2048
	s_add_u32 s10, s10, 0x1000
	s_addc_u32 s11, s11, 0
	global_atomic_add v3, v2, s[10:11]
	global_atomic_add v3, v2, s[10:11] offset:2048
	s_mov_b64 exec, s[6:7]
